# sparse tile loop: the second tile-top wait (in front of q_unstage) also counts only the loads, not the previous tile's nine PART stores; v75 otherwise
# speedup vs baseline: 1.0065x; 1.0065x over previous
.Lspa_wd:
	v_mov_b32_e32 v206, v147
	s_mov_b64 s[6:7], 0
	s_cmp_eq_u32 s65, s12
	s_mov_b64 s[30:31], -1
	s_cbranch_scc1 .LBB0_826
	s_ashr_i32 s6, s65, 8
	s_ashr_i32 s7, s6, 31
	s_lshl_b32 s12, s65, 8
	s_lshl_b64 s[6:7], s[6:7], 13
	s_and_b32 s12, s12, 0x1f00
	s_or_b32 s6, s6, s12
	s_lshl_b32 s12, s68, 8
	s_and_b32 s12, s12, 0x700
	s_add_u32 s30, s39, s12
	v_lshl_add_u64 v[6:7], s[6:7], 0, v[144:145]
	s_addc_u32 s31, s44, 0
	v_lshlrev_b64 v[6:7], 11, v[6:7]
	v_lshl_add_u64 v[6:7], s[30:31], 0, v[6:7]
	v_mov_b32_e32 v147, v177
	s_mov_b32 m0, s47
	v_mov_b32_e32 v1, s7
	v_or_b32_e32 v0, s6, v187
	v_lshl_add_u64 v[6:7], v[6:7], 0, v[146:147]
	s_waitcnt lgkmcnt(0)
	s_barrier
	global_load_lds_dwordx4 v[6:7], off
	v_lshl_add_u64 v[6:7], v[0:1], 0, s[10:11]
	v_lshl_add_u64 v[4:5], v[180:181], 0, s[12:13]
	v_lshlrev_b64 v[6:7], 11, v[6:7]
	v_lshl_add_u64 v[6:7], v[4:5], 0, v[6:7]
	s_mov_b32 m0, s50
	v_mov_b32_e32 v151, v177
	global_load_lds_dwordx4 v[6:7], off
	v_lshl_add_u64 v[6:7], s[6:7], 0, v[148:149]
	v_lshlrev_b64 v[6:7], 11, v[6:7]
	v_lshl_add_u64 v[6:7], s[30:31], 0, v[6:7]
	v_lshl_add_u64 v[6:7], v[6:7], 0, v[150:151]
	s_mov_b32 m0, s51
	v_mov_b32_e32 v155, v177
	global_load_lds_dwordx4 v[6:7], off
	v_lshl_add_u64 v[6:7], v[0:1], 0, s[16:17]
	v_lshlrev_b64 v[6:7], 11, v[6:7]
	v_lshl_add_u64 v[6:7], v[4:5], 0, v[6:7]
	s_mov_b32 m0, s52
	v_mov_b32_e32 v159, v177
	global_load_lds_dwordx4 v[6:7], off
	v_lshl_add_u64 v[6:7], s[6:7], 0, v[152:153]
	v_lshlrev_b64 v[6:7], 11, v[6:7]
	v_lshl_add_u64 v[6:7], s[30:31], 0, v[6:7]
	v_lshl_add_u64 v[6:7], v[6:7], 0, v[154:155]
	s_mov_b32 m0, s53
	v_mov_b32_e32 v163, v177
	global_load_lds_dwordx4 v[6:7], off
	v_lshl_add_u64 v[6:7], v[0:1], 0, s[18:19]
	v_lshlrev_b64 v[6:7], 11, v[6:7]
	v_lshl_add_u64 v[6:7], v[4:5], 0, v[6:7]
	s_mov_b32 m0, s54
	v_mov_b32_e32 v167, v177
	global_load_lds_dwordx4 v[6:7], off
	v_lshl_add_u64 v[6:7], s[6:7], 0, v[156:157]
	v_lshlrev_b64 v[6:7], 11, v[6:7]
	v_lshl_add_u64 v[6:7], s[30:31], 0, v[6:7]
	v_lshl_add_u64 v[6:7], v[6:7], 0, v[158:159]
	s_mov_b32 m0, s55
	v_mov_b32_e32 v171, v177
	global_load_lds_dwordx4 v[6:7], off
	v_lshl_add_u64 v[6:7], v[0:1], 0, s[20:21]
	v_lshlrev_b64 v[6:7], 11, v[6:7]
	v_lshl_add_u64 v[6:7], v[4:5], 0, v[6:7]
	s_mov_b32 m0, s56
	v_mov_b32_e32 v175, v177
	global_load_lds_dwordx4 v[6:7], off
	v_lshl_add_u64 v[6:7], s[6:7], 0, v[160:161]
	v_lshlrev_b64 v[6:7], 11, v[6:7]
	v_lshl_add_u64 v[6:7], s[30:31], 0, v[6:7]
	v_lshl_add_u64 v[6:7], v[6:7], 0, v[162:163]
	s_mov_b32 m0, s57
	s_nop 0
	global_load_lds_dwordx4 v[6:7], off
	v_lshl_add_u64 v[6:7], v[0:1], 0, s[22:23]
	v_lshlrev_b64 v[6:7], 11, v[6:7]
	v_lshl_add_u64 v[6:7], v[4:5], 0, v[6:7]
	s_mov_b32 m0, s58
	s_nop 0
	global_load_lds_dwordx4 v[6:7], off
	v_lshl_add_u64 v[6:7], s[6:7], 0, v[164:165]
	v_lshlrev_b64 v[6:7], 11, v[6:7]
	v_lshl_add_u64 v[6:7], s[30:31], 0, v[6:7]
	v_lshl_add_u64 v[6:7], v[6:7], 0, v[166:167]
	s_mov_b32 m0, s59
	s_nop 0
	global_load_lds_dwordx4 v[6:7], off
	v_lshl_add_u64 v[6:7], v[0:1], 0, s[24:25]
	v_lshlrev_b64 v[6:7], 11, v[6:7]
	v_lshl_add_u64 v[6:7], v[4:5], 0, v[6:7]
	s_mov_b32 m0, s60
	s_nop 0
	global_load_lds_dwordx4 v[6:7], off
	v_lshl_add_u64 v[6:7], s[6:7], 0, v[168:169]
	v_lshlrev_b64 v[6:7], 11, v[6:7]
	v_lshl_add_u64 v[6:7], s[30:31], 0, v[6:7]
	v_lshl_add_u64 v[6:7], v[6:7], 0, v[170:171]
	s_mov_b32 m0, s61
	s_nop 0
	global_load_lds_dwordx4 v[6:7], off
	v_lshl_add_u64 v[6:7], v[0:1], 0, s[26:27]
	v_lshlrev_b64 v[6:7], 11, v[6:7]
	v_lshl_add_u64 v[6:7], v[4:5], 0, v[6:7]
	s_mov_b32 m0, s62
	v_lshl_add_u64 v[0:1], v[0:1], 0, s[28:29]
	global_load_lds_dwordx4 v[6:7], off
	v_lshl_add_u64 v[6:7], s[6:7], 0, v[172:173]
	v_lshlrev_b64 v[6:7], 11, v[6:7]
	v_lshl_add_u64 v[6:7], s[30:31], 0, v[6:7]
	v_lshl_add_u64 v[6:7], v[6:7], 0, v[174:175]
	s_mov_b32 m0, s63
	v_lshlrev_b64 v[0:1], 11, v[0:1]
	global_load_lds_dwordx4 v[6:7], off
	v_lshl_add_u64 v[0:1], v[4:5], 0, v[0:1]
	s_mov_b32 m0, s64
	s_mov_b64 s[30:31], 0
	global_load_lds_dwordx4 v[0:1], off
	s_waitcnt vmcnt(0)
	s_mov_b64 s[6:7], -1
	s_waitcnt vmcnt(0) lgkmcnt(0)
	s_barrier

.LBB0_831:
	s_cmp_eq_u32 s98, 9
	s_cbranch_scc1 .Lspb_w9
	s_waitcnt vmcnt(0)
	s_branch .Lspb_wd

.Lspb_wd:
	s_mov_b32 s98, 0
	ds_write_b128 v201, v[92:95]
	ds_write_b128 v201, v[108:111] offset:1280
	s_waitcnt lgkmcnt(0)
	ds_read_b128 v[112:115], v202
	ds_read_b128 v[116:119], v202 offset:32
	s_waitcnt lgkmcnt(0)
	ds_write_b128 v201, v[104:107]
	ds_write_b128 v201, v[88:91] offset:1280
	s_waitcnt lgkmcnt(0)
	ds_read_b128 v[120:123], v202
	ds_read_b128 v[124:127], v202 offset:32
	s_waitcnt lgkmcnt(0)
	ds_write_b128 v201, v[84:87]
	ds_write_b128 v201, v[100:103] offset:1280
	s_waitcnt lgkmcnt(0)
	ds_read_b128 v[128:131], v202
	ds_read_b128 v[132:135], v202 offset:32
	s_waitcnt lgkmcnt(0)
	ds_write_b128 v201, v[96:99]
	ds_write_b128 v201, v[80:83] offset:1280
	s_waitcnt lgkmcnt(0)
	ds_read_b128 v[136:139], v202
	ds_read_b128 v[140:143], v202 offset:32
	s_waitcnt lgkmcnt(0)
	s_add_i32 s67, s66, 1
	v_cmp_ge_u32_e64 s[6:7], s67, v186
	s_and_b64 vcc, exec, s[6:7]
	s_cbranch_vccnz .LBB0_833
	ds_bpermute_b32 v0, v188, v206
	ds_bpermute_b32 v4, v189, v206
	s_ashr_i32 s8, s38, 8
	s_ashr_i32 s9, s8, 31
	s_lshl_b64 s[8:9], s[8:9], 13
	s_waitcnt lgkmcnt(1)
	v_lshrrev_b32_e32 v1, 2, v0
	v_cmp_ne_u32_e32 vcc, -1, v0
	s_waitcnt lgkmcnt(0)
	v_lshrrev_b32_e32 v5, 2, v4
	s_lshl_b32 s12, s38, 3
	v_cndmask_b32_e32 v176, 0, v1, vcc
	v_cmp_ne_u32_e32 vcc, -1, v4
	v_lshl_add_u64 v[0:1], s[8:9], 0, v[176:177]
	v_lshlrev_b64 v[0:1], 11, v[0:1]
	v_cndmask_b32_e32 v176, 0, v5, vcc
	v_lshl_add_u64 v[4:5], s[8:9], 0, v[176:177]
	v_lshl_add_u64 v[0:1], s[34:35], 0, v[0:1]
	s_and_b32 s12, s12, 0x700
	v_lshlrev_b64 v[4:5], 11, v[4:5]
	v_lshl_add_u64 v[0:1], v[0:1], 0, s[12:13]
	v_mov_b32_e32 v185, v177
	v_lshl_add_u64 v[4:5], s[34:35], 0, v[4:5]
	v_lshl_add_u64 v[0:1], v[0:1], 0, v[184:185]
	v_lshl_add_u64 v[4:5], v[4:5], 0, s[12:13]
	v_lshl_add_u64 v[4:5], v[4:5], 0, v[184:185]
	global_load_dwordx4 v[92:95], v[0:1], off
	global_load_dwordx4 v[104:107], v[0:1], off offset:64
	global_load_dwordx4 v[108:111], v[4:5], off
	global_load_dwordx4 v[88:91], v[4:5], off offset:64
	global_load_dwordx4 v[84:87], v[0:1], off offset:128
	global_load_dwordx4 v[96:99], v[0:1], off offset:192
	global_load_dwordx4 v[100:103], v[4:5], off offset:128
	global_load_dwordx4 v[80:83], v[4:5], off offset:192
